# P7 SwiGLU epilogue restructured: all row-stat loads issued up front (quarter per lane + permlane swaps), no serialized load-store chains; compute dtype unchanged
# speedup vs baseline: 1.0109x; 1.0109x over previous
.LBB0_1034:
	ds_read_b128 v[146:149], v156
	ds_read_b128 v[150:153], v156 offset:1024
	ds_read_b128 v[162:165], v156 offset:2048
	ds_read_b128 v[166:169], v156 offset:3072
	ds_read_b128 v[170:173], v157
	ds_read_b128 v[174:177], v157 offset:1024
	ds_read_b128 v[178:181], v157 offset:2048
	ds_read_b128 v[182:185], v157 offset:3072
	s_add_u32 s42, s40, 0xfffc0080
	s_addc_u32 s43, s41, -1
	s_cmp_eq_u32 s63, 12
	s_cselect_b32 s45, s29, s43
	s_cselect_b32 s44, s59, s42
	s_cselect_b32 s43, s27, s62
	s_cselect_b32 s42, s60, s61
	v_lshl_add_u64 v[220:221], s[40:41], 0, v[138:139]
	s_add_i32 m0, s48, 0xc000
	ds_read_b128 v[186:189], v158
	ds_read_b128 v[190:193], v158 offset:1024
	ds_read_b128 v[194:197], v158 offset:2048
	ds_read_b128 v[200:203], v158 offset:3072
	ds_read_b128 v[204:207], v158 offset:4096
	ds_read_b128 v[208:211], v158 offset:5120
	ds_read_b128 v[212:215], v158 offset:6144
	ds_read_b128 v[216:219], v158 offset:7168
	global_load_lds_dwordx4 v[220:221], off
	v_lshl_add_u64 v[220:221], s[40:41], 0, v[140:141]
	s_add_i32 m0, s48, 0xe000
	s_nop 0
	global_load_lds_dwordx4 v[220:221], off
	s_waitcnt vmcnt(8)
	s_waitcnt lgkmcnt(0)
	s_barrier
	s_setprio 1
	s_waitcnt lgkmcnt(0)
	v_mfma_f32_16x16x32_bf16 v[126:129], v[146:149], v[186:189], v[126:129]
	v_mfma_f32_16x16x32_bf16 v[122:125], v[162:165], v[186:189], v[122:125]
	v_mfma_f32_16x16x32_bf16 v[110:113], v[146:149], v[194:197], v[110:113]
	v_mfma_f32_16x16x32_bf16 v[106:109], v[162:165], v[194:197], v[106:109]
	v_mfma_f32_16x16x32_bf16 v[94:97], v[146:149], v[204:207], v[94:97]
	v_mfma_f32_16x16x32_bf16 v[90:93], v[162:165], v[204:207], v[90:93]
	v_mfma_f32_16x16x32_bf16 v[78:81], v[146:149], v[212:215], v[78:81]
	v_mfma_f32_16x16x32_bf16 v[74:77], v[162:165], v[212:215], v[74:77]
	v_mfma_f32_16x16x32_bf16 v[126:129], v[150:153], v[190:193], v[126:129]
	v_mfma_f32_16x16x32_bf16 v[122:125], v[166:169], v[190:193], v[122:125]
	v_mfma_f32_16x16x32_bf16 v[110:113], v[150:153], v[200:203], v[110:113]
	v_mfma_f32_16x16x32_bf16 v[106:109], v[166:169], v[200:203], v[106:109]
	v_mfma_f32_16x16x32_bf16 v[94:97], v[150:153], v[208:211], v[94:97]
	v_mfma_f32_16x16x32_bf16 v[90:93], v[166:169], v[208:211], v[90:93]
	v_mfma_f32_16x16x32_bf16 v[78:81], v[150:153], v[216:219], v[78:81]
	v_mfma_f32_16x16x32_bf16 v[74:77], v[166:169], v[216:219], v[74:77]
	s_setprio 0
	s_setprio 1
	v_mfma_f32_16x16x32_bf16 v[118:121], v[170:173], v[186:189], v[118:121]
	v_mfma_f32_16x16x32_bf16 v[114:117], v[178:181], v[186:189], v[114:117]
	v_mfma_f32_16x16x32_bf16 v[102:105], v[170:173], v[194:197], v[102:105]
	v_mfma_f32_16x16x32_bf16 v[98:101], v[178:181], v[194:197], v[98:101]
	v_mfma_f32_16x16x32_bf16 v[86:89], v[170:173], v[204:207], v[86:89]
	v_mfma_f32_16x16x32_bf16 v[82:85], v[178:181], v[204:207], v[82:85]
	v_mfma_f32_16x16x32_bf16 v[70:73], v[170:173], v[212:215], v[70:73]
	v_mfma_f32_16x16x32_bf16 v[66:69], v[178:181], v[212:215], v[66:69]
	v_mfma_f32_16x16x32_bf16 v[118:121], v[174:177], v[190:193], v[118:121]
	v_mfma_f32_16x16x32_bf16 v[114:117], v[182:185], v[190:193], v[114:117]
	v_mfma_f32_16x16x32_bf16 v[102:105], v[174:177], v[200:203], v[102:105]
	v_mfma_f32_16x16x32_bf16 v[98:101], v[182:185], v[200:203], v[98:101]
	v_mfma_f32_16x16x32_bf16 v[86:89], v[174:177], v[208:211], v[86:89]
	v_mfma_f32_16x16x32_bf16 v[82:85], v[182:185], v[208:211], v[82:85]
	v_mfma_f32_16x16x32_bf16 v[70:73], v[174:177], v[216:219], v[70:73]
	v_mfma_f32_16x16x32_bf16 v[66:69], v[182:185], v[216:219], v[66:69]
	s_setprio 0
	s_barrier
	s_add_i32 s64, s55, s46
	v_lshl_add_u64 v[220:221], s[42:43], 0, v[134:135]
	s_mov_b32 m0, s64
	ds_read_b128 v[186:189], v158 offset:16384
	ds_read_b128 v[190:193], v158 offset:17408
	ds_read_b128 v[194:197], v158 offset:18432
	ds_read_b128 v[200:203], v158 offset:19456
	ds_read_b128 v[204:207], v158 offset:20480
	ds_read_b128 v[208:211], v158 offset:21504
	ds_read_b128 v[212:215], v158 offset:22528
	ds_read_b128 v[216:219], v158 offset:23552
	global_load_lds_dwordx4 v[220:221], off
	s_add_i32 m0, s64, 0x2000
	s_add_u32 s64, s42, 0x40000
	v_lshl_add_u64 v[222:223], s[42:43], 0, v[130:131]
	s_addc_u32 s65, s43, 0
	s_add_i32 s66, s56, s46
	global_load_lds_dwordx4 v[222:223], off
	v_lshl_add_u64 v[224:225], s[64:65], 0, v[134:135]
	s_mov_b32 m0, s66
	v_lshl_add_u64 v[226:227], s[44:45], 0, v[132:133]
	global_load_lds_dwordx4 v[224:225], off
	v_lshl_add_u64 v[224:225], s[64:65], 0, v[130:131]
	s_add_i32 m0, s66, 0x2000
	s_nop 0
	global_load_lds_dwordx4 v[224:225], off
	v_lshl_add_u64 v[224:225], s[44:45], 0, v[136:137]
	s_mov_b32 m0, s48
	s_nop 0
	global_load_lds_dwordx4 v[224:225], off
	s_mov_b32 m0, s49
	s_nop 0
	global_load_lds_dwordx4 v[226:227], off
	s_waitcnt vmcnt(8)
	s_waitcnt lgkmcnt(0)
	s_barrier
	s_setprio 1
	s_waitcnt lgkmcnt(0)
	v_mfma_f32_16x16x32_bf16 v[62:65], v[146:149], v[186:189], v[62:65]
	v_mfma_f32_16x16x32_bf16 v[58:61], v[162:165], v[186:189], v[58:61]
	v_mfma_f32_16x16x32_bf16 v[46:49], v[146:149], v[194:197], v[46:49]
	v_mfma_f32_16x16x32_bf16 v[42:45], v[162:165], v[194:197], v[42:45]
	v_mfma_f32_16x16x32_bf16 v[30:33], v[146:149], v[204:207], v[30:33]
	v_mfma_f32_16x16x32_bf16 v[26:29], v[162:165], v[204:207], v[26:29]
	v_mfma_f32_16x16x32_bf16 v[14:17], v[146:149], v[212:215], v[14:17]
	v_mfma_f32_16x16x32_bf16 v[10:13], v[162:165], v[212:215], v[10:13]
	v_mfma_f32_16x16x32_bf16 v[62:65], v[150:153], v[190:193], v[62:65]
	v_mfma_f32_16x16x32_bf16 v[58:61], v[166:169], v[190:193], v[58:61]
	v_mfma_f32_16x16x32_bf16 v[46:49], v[150:153], v[200:203], v[46:49]
	v_mfma_f32_16x16x32_bf16 v[42:45], v[166:169], v[200:203], v[42:45]
	v_mfma_f32_16x16x32_bf16 v[30:33], v[150:153], v[208:211], v[30:33]
	v_mfma_f32_16x16x32_bf16 v[26:29], v[166:169], v[208:211], v[26:29]
	v_mfma_f32_16x16x32_bf16 v[14:17], v[150:153], v[216:219], v[14:17]
	v_mfma_f32_16x16x32_bf16 v[10:13], v[166:169], v[216:219], v[10:13]
	s_setprio 0
	s_setprio 1
	v_mfma_f32_16x16x32_bf16 v[54:57], v[170:173], v[186:189], v[54:57]
	v_mfma_f32_16x16x32_bf16 v[50:53], v[178:181], v[186:189], v[50:53]
	v_mfma_f32_16x16x32_bf16 v[38:41], v[170:173], v[194:197], v[38:41]
	v_mfma_f32_16x16x32_bf16 v[34:37], v[178:181], v[194:197], v[34:37]
	v_mfma_f32_16x16x32_bf16 v[22:25], v[170:173], v[204:207], v[22:25]
	v_mfma_f32_16x16x32_bf16 v[18:21], v[178:181], v[204:207], v[18:21]
	v_mfma_f32_16x16x32_bf16 v[6:9], v[170:173], v[212:215], v[6:9]
	v_mfma_f32_16x16x32_bf16 v[2:5], v[178:181], v[212:215], v[2:5]
	v_mfma_f32_16x16x32_bf16 v[54:57], v[174:177], v[190:193], v[54:57]
	v_mfma_f32_16x16x32_bf16 v[50:53], v[182:185], v[190:193], v[50:53]
	v_mfma_f32_16x16x32_bf16 v[38:41], v[174:177], v[200:203], v[38:41]
	v_mfma_f32_16x16x32_bf16 v[34:37], v[182:185], v[200:203], v[34:37]
	v_mfma_f32_16x16x32_bf16 v[22:25], v[174:177], v[208:211], v[22:25]
	v_mfma_f32_16x16x32_bf16 v[18:21], v[182:185], v[208:211], v[18:21]
	v_mfma_f32_16x16x32_bf16 v[6:9], v[174:177], v[216:219], v[6:9]
	v_mfma_f32_16x16x32_bf16 v[2:5], v[182:185], v[216:219], v[2:5]
	s_setprio 0
	s_barrier
	s_add_i32 s64, 0, 0x18000
	v_add_u32_e32 v161, s64, v154
	s_add_i32 s65, 0, 0x1c000
	ds_read_b128 v[146:149], v161
	ds_read_b128 v[150:153], v161 offset:1024
	ds_read_b128 v[162:165], v161 offset:2048
	ds_read_b128 v[166:169], v161 offset:3072
	v_add_u32_e32 v161, s65, v154
	ds_read_b128 v[170:173], v161
	ds_read_b128 v[174:177], v161 offset:1024
	ds_read_b128 v[178:181], v161 offset:2048
	ds_read_b128 v[182:185], v161 offset:3072
	s_add_u32 s44, s44, 0x40000
	s_addc_u32 s45, s45, 0
	s_mov_b32 m0, s50
	v_lshl_add_u64 v[228:229], s[44:45], 0, v[136:137]
	ds_read_b128 v[186:189], v158 offset:32768
	ds_read_b128 v[190:193], v158 offset:33792
	ds_read_b128 v[194:197], v158 offset:34816
	ds_read_b128 v[200:203], v158 offset:35840
	ds_read_b128 v[204:207], v158 offset:36864
	ds_read_b128 v[208:211], v158 offset:37888
	ds_read_b128 v[212:215], v158 offset:38912
	ds_read_b128 v[216:219], v158 offset:39936
	global_load_lds_dwordx4 v[228:229], off
	v_lshl_add_u64 v[228:229], s[44:45], 0, v[132:133]
	s_mov_b32 m0, s51
	s_nop 0
	global_load_lds_dwordx4 v[228:229], off
	s_waitcnt vmcnt(8)
	s_waitcnt lgkmcnt(0)
	s_barrier
	s_setprio 1
	s_waitcnt lgkmcnt(0)
	v_mfma_f32_16x16x32_bf16 v[126:129], v[146:149], v[186:189], v[126:129]
	v_mfma_f32_16x16x32_bf16 v[122:125], v[162:165], v[186:189], v[122:125]
	v_mfma_f32_16x16x32_bf16 v[110:113], v[146:149], v[194:197], v[110:113]
	v_mfma_f32_16x16x32_bf16 v[106:109], v[162:165], v[194:197], v[106:109]
	v_mfma_f32_16x16x32_bf16 v[94:97], v[146:149], v[204:207], v[94:97]
	v_mfma_f32_16x16x32_bf16 v[90:93], v[162:165], v[204:207], v[90:93]
	v_mfma_f32_16x16x32_bf16 v[78:81], v[146:149], v[212:215], v[78:81]
	v_mfma_f32_16x16x32_bf16 v[74:77], v[162:165], v[212:215], v[74:77]
	v_mfma_f32_16x16x32_bf16 v[126:129], v[150:153], v[190:193], v[126:129]
	v_mfma_f32_16x16x32_bf16 v[122:125], v[166:169], v[190:193], v[122:125]
	v_mfma_f32_16x16x32_bf16 v[110:113], v[150:153], v[200:203], v[110:113]
	v_mfma_f32_16x16x32_bf16 v[106:109], v[166:169], v[200:203], v[106:109]
	v_mfma_f32_16x16x32_bf16 v[94:97], v[150:153], v[208:211], v[94:97]
	v_mfma_f32_16x16x32_bf16 v[90:93], v[166:169], v[208:211], v[90:93]
	v_mfma_f32_16x16x32_bf16 v[78:81], v[150:153], v[216:219], v[78:81]
	v_mfma_f32_16x16x32_bf16 v[74:77], v[166:169], v[216:219], v[74:77]
	s_setprio 0
	s_setprio 1
	v_mfma_f32_16x16x32_bf16 v[118:121], v[170:173], v[186:189], v[118:121]
	v_mfma_f32_16x16x32_bf16 v[114:117], v[178:181], v[186:189], v[114:117]
	v_mfma_f32_16x16x32_bf16 v[102:105], v[170:173], v[194:197], v[102:105]
	v_mfma_f32_16x16x32_bf16 v[98:101], v[178:181], v[194:197], v[98:101]
	v_mfma_f32_16x16x32_bf16 v[86:89], v[170:173], v[204:207], v[86:89]
	v_mfma_f32_16x16x32_bf16 v[82:85], v[178:181], v[204:207], v[82:85]
	v_mfma_f32_16x16x32_bf16 v[70:73], v[170:173], v[212:215], v[70:73]
	v_mfma_f32_16x16x32_bf16 v[66:69], v[178:181], v[212:215], v[66:69]
	v_mfma_f32_16x16x32_bf16 v[118:121], v[174:177], v[190:193], v[118:121]
	v_mfma_f32_16x16x32_bf16 v[114:117], v[182:185], v[190:193], v[114:117]
	v_mfma_f32_16x16x32_bf16 v[102:105], v[174:177], v[200:203], v[102:105]
	v_mfma_f32_16x16x32_bf16 v[98:101], v[182:185], v[200:203], v[98:101]
	v_mfma_f32_16x16x32_bf16 v[86:89], v[174:177], v[208:211], v[86:89]
	v_mfma_f32_16x16x32_bf16 v[82:85], v[182:185], v[208:211], v[82:85]
	v_mfma_f32_16x16x32_bf16 v[70:73], v[174:177], v[216:219], v[70:73]
	v_mfma_f32_16x16x32_bf16 v[66:69], v[182:185], v[216:219], v[66:69]
	s_setprio 0
	s_barrier
; #define PG8_BAR __builtin_amdgcn_s_barrier()
; template <class Epi, bool HOOK = false>
; DI void gemm_phase(LAS unsigned char* lds, const Gemm g, const StaticOrder& S, const Epi& E) {
;     ...
;         if constexpr (HOOK) {
;             for (int t = 0; t < (nt >> 1); t += 2) PG8_KBODY();
;             E.hook(acc, cur, wr, wc, fr, fq);
;             for (int t = (nt >> 1); t < nt; t += 2) PG8_KBODY();
;         } else {
;             for (int t = 0; t < nt; t += 2) PG8_KBODY();
;         }
;     ...
;         if (wr == 0) PG8_BAR;
;     DI void operator()(const Acc& acc, const Unit& u, int wr, int wc, int fr, int fq) const {
;     ...
;                 const int r = row0 + ai * 128 + m * 16;
;                 const f32x4* sp = (const f32x4*)(SS + (size_t)r * 16);
;                 const f32x4 s0 = sp[0], s1 = sp[1], s2 = sp[2], s3 = sp[3];
	s_add_i32 s44, s64, s46
	v_lshl_add_u64 v[220:221], v[220:221], 0, s[16:17]
	s_mov_b32 m0, s44
	ds_read_b128 v[186:189], v158 offset:49152
	ds_read_b128 v[190:193], v158 offset:50176
	ds_read_b128 v[194:197], v158 offset:51200
	ds_read_b128 v[200:203], v158 offset:52224
	ds_read_b128 v[204:207], v158 offset:53248
	ds_read_b128 v[208:211], v158 offset:54272
	ds_read_b128 v[212:215], v158 offset:55296
	ds_read_b128 v[216:219], v158 offset:56320
	global_load_lds_dwordx4 v[220:221], off
	s_add_i32 m0, s44, 0x2000
	s_add_u32 s42, s42, 0x40080
	v_lshl_add_u64 v[220:221], v[222:223], 0, s[16:17]
	s_addc_u32 s43, s43, 0
	s_add_i32 s44, s65, s46
	global_load_lds_dwordx4 v[220:221], off
	v_lshl_add_u64 v[220:221], s[42:43], 0, v[134:135]
	s_mov_b32 m0, s44
	s_nop 0
	global_load_lds_dwordx4 v[220:221], off
	v_lshl_add_u64 v[220:221], s[42:43], 0, v[130:131]
	s_add_i32 m0, s44, 0x2000
	s_nop 0
	global_load_lds_dwordx4 v[220:221], off
	v_lshl_add_u64 v[220:221], v[224:225], 0, s[16:17]
	s_mov_b32 m0, s53
	s_nop 0
	global_load_lds_dwordx4 v[220:221], off
	v_lshl_add_u64 v[220:221], v[226:227], 0, s[16:17]
	s_mov_b32 m0, s54
	s_nop 0
	global_load_lds_dwordx4 v[220:221], off
	s_waitcnt vmcnt(8)
	s_waitcnt lgkmcnt(0)
	s_barrier
	s_setprio 1
	s_waitcnt lgkmcnt(0)
	v_mfma_f32_16x16x32_bf16 v[62:65], v[146:149], v[186:189], v[62:65]
	v_mfma_f32_16x16x32_bf16 v[58:61], v[162:165], v[186:189], v[58:61]
	v_mfma_f32_16x16x32_bf16 v[46:49], v[146:149], v[194:197], v[46:49]
	v_mfma_f32_16x16x32_bf16 v[42:45], v[162:165], v[194:197], v[42:45]
	v_mfma_f32_16x16x32_bf16 v[30:33], v[146:149], v[204:207], v[30:33]
	v_mfma_f32_16x16x32_bf16 v[26:29], v[162:165], v[204:207], v[26:29]
	v_mfma_f32_16x16x32_bf16 v[14:17], v[146:149], v[212:215], v[14:17]
	v_mfma_f32_16x16x32_bf16 v[10:13], v[162:165], v[212:215], v[10:13]
	v_mfma_f32_16x16x32_bf16 v[62:65], v[150:153], v[190:193], v[62:65]
	v_mfma_f32_16x16x32_bf16 v[58:61], v[166:169], v[190:193], v[58:61]
	v_mfma_f32_16x16x32_bf16 v[46:49], v[150:153], v[200:203], v[46:49]
	v_mfma_f32_16x16x32_bf16 v[42:45], v[166:169], v[200:203], v[42:45]
	v_mfma_f32_16x16x32_bf16 v[30:33], v[150:153], v[208:211], v[30:33]
	v_mfma_f32_16x16x32_bf16 v[26:29], v[166:169], v[208:211], v[26:29]
	v_mfma_f32_16x16x32_bf16 v[14:17], v[150:153], v[216:219], v[14:17]
	v_mfma_f32_16x16x32_bf16 v[10:13], v[166:169], v[216:219], v[10:13]
	s_setprio 0
	s_setprio 1
	v_mfma_f32_16x16x32_bf16 v[54:57], v[170:173], v[186:189], v[54:57]
	v_mfma_f32_16x16x32_bf16 v[50:53], v[178:181], v[186:189], v[50:53]
	v_mfma_f32_16x16x32_bf16 v[38:41], v[170:173], v[194:197], v[38:41]
	v_mfma_f32_16x16x32_bf16 v[34:37], v[178:181], v[194:197], v[34:37]
	v_mfma_f32_16x16x32_bf16 v[22:25], v[170:173], v[204:207], v[22:25]
	v_mfma_f32_16x16x32_bf16 v[18:21], v[178:181], v[204:207], v[18:21]
	v_mfma_f32_16x16x32_bf16 v[6:9], v[170:173], v[212:215], v[6:9]
	v_mfma_f32_16x16x32_bf16 v[2:5], v[178:181], v[212:215], v[2:5]
	v_mfma_f32_16x16x32_bf16 v[54:57], v[174:177], v[190:193], v[54:57]
	v_mfma_f32_16x16x32_bf16 v[50:53], v[182:185], v[190:193], v[50:53]
	v_mfma_f32_16x16x32_bf16 v[38:41], v[174:177], v[200:203], v[38:41]
	v_mfma_f32_16x16x32_bf16 v[34:37], v[182:185], v[200:203], v[34:37]
	v_mfma_f32_16x16x32_bf16 v[22:25], v[174:177], v[208:211], v[22:25]
	v_mfma_f32_16x16x32_bf16 v[18:21], v[182:185], v[208:211], v[18:21]
	v_mfma_f32_16x16x32_bf16 v[6:9], v[174:177], v[216:219], v[6:9]
	v_mfma_f32_16x16x32_bf16 v[2:5], v[182:185], v[216:219], v[2:5]
	s_setprio 0
	s_barrier
	s_add_i32 s63, s63, 2
	s_add_u32 s40, s40, 0x100
	s_addc_u32 s41, s41, 0
	s_add_u32 s61, s61, 0x100
	s_addc_u32 s62, s62, 0
	s_cmp_gt_u32 s63, 13
	s_cbranch_scc0 .LBB0_1034
	v_lshl_add_u32 v150, s6, 8, v1
	v_and_b32_e32 v151, 12, v155
	v_lshlrev_b32_e32 v152, 6, v150
	v_lshl_add_u32 v152, v151, 2, v152
	v_add_u32_e32 v153, 0x2000, v152
	global_load_dwordx4 v[162:165], v152, s[14:15]
	global_load_dwordx4 v[166:169], v152, s[14:15] offset:1024
	global_load_dwordx4 v[170:173], v152, s[14:15] offset:2048
	global_load_dwordx4 v[174:177], v152, s[14:15] offset:3072
	global_load_dwordx4 v[178:181], v153, s[14:15]
	global_load_dwordx4 v[182:185], v153, s[14:15] offset:1024
	global_load_dwordx4 v[186:189], v153, s[14:15] offset:2048
	global_load_dwordx4 v[190:193], v153, s[14:15] offset:3072
	v_lshl_or_b32 v148, s7, 7, v155
	v_lshlrev_b32_e32 v148, 1, v148
	v_mad_u32_u24 v161, v150, s58, v148
	s_and_b64 vcc, exec, s[20:21]
	s_cbranch_vccz .LBB0_1037
	s_barrier
; DI float sigmoidf_(float x) { return __builtin_amdgcn_rcpf(1.0f + __expf(-x)); }
;     DI void operator()(const Acc& acc, const Unit& u, int wr, int wc, int fr, int fq) const {
;     ...
;                 const int r = row0 + ai * 128 + m * 16;
;                 const f32x4* sp = (const f32x4*)(SS + (size_t)r * 16);
;                 const f32x4 s0 = sp[0], s1 = sp[1], s2 = sp[2], s3 = sp[3];
;                 const float tot = ((s0[0] + s0[1]) + (s0[2] + s0[3])) + ((s1[0] + s1[1]) + (s1[2] + s1[3])) + ((s2[0] + s2[1]) + (s2[2] + s2[3])) + ((s3[0] + s3[1]) + (s3[2] + s3[3]));
;                 const float rr = 1.0f / sqrtf(tot * (1.0f / DM) + EPS);
; #pragma unroll
;                 for (int bj = 0; bj < 2; ++bj) {
;                     const int f0 = u.pn * 128 + bj * 64 + wc * 16 + 4 * fq;
;                     const f32x4 g = acc[ai][bj][m][0] * rr, up = acc[ai][bj][m][1] * rr;
;                     float o[4];
; #pragma unroll
;                     for (int i = 0; i < 4; ++i) o[i] = g[i] * sigmoidf_(g[i]) * up[i];
.LBB0_1037:
	s_waitcnt vmcnt(0)
	v_add_f32_e32 v162, v162, v163
	v_add_f32_e32 v164, v164, v165
	v_add_f32_e32 v166, v166, v167
	v_add_f32_e32 v168, v168, v169
	v_add_f32_e32 v170, v170, v171
	v_add_f32_e32 v172, v172, v173
	v_add_f32_e32 v174, v174, v175
	v_add_f32_e32 v176, v176, v177
	v_add_f32_e32 v178, v178, v179
	v_add_f32_e32 v180, v180, v181
	v_add_f32_e32 v182, v182, v183
	v_add_f32_e32 v184, v184, v185
	v_add_f32_e32 v186, v186, v187
	v_add_f32_e32 v188, v188, v189
	v_add_f32_e32 v190, v190, v191
	v_add_f32_e32 v192, v192, v193
	v_add_f32_e32 v162, v162, v164
	v_add_f32_e32 v166, v166, v168
	v_add_f32_e32 v170, v170, v172
	v_add_f32_e32 v174, v174, v176
	v_add_f32_e32 v178, v178, v180
	v_add_f32_e32 v182, v182, v184
	v_add_f32_e32 v186, v186, v188
	v_add_f32_e32 v190, v190, v192
	v_mov_b32_e32 v163, v162
	v_mov_b32_e32 v167, v166
	v_mov_b32_e32 v171, v170
	v_mov_b32_e32 v175, v174
	v_mov_b32_e32 v179, v178
	v_mov_b32_e32 v183, v182
	v_mov_b32_e32 v187, v186
	v_mov_b32_e32 v191, v190
	s_nop 1
	v_permlane16_swap_b32_e32 v162, v163
	v_permlane16_swap_b32_e32 v166, v167
	v_permlane16_swap_b32_e32 v170, v171
	v_permlane16_swap_b32_e32 v174, v175
	v_permlane16_swap_b32_e32 v178, v179
	v_permlane16_swap_b32_e32 v182, v183
	v_permlane16_swap_b32_e32 v186, v187
	v_permlane16_swap_b32_e32 v190, v191
	v_mov_b32_e32 v164, v162
	v_mov_b32_e32 v165, v163
	v_mov_b32_e32 v168, v166
	v_mov_b32_e32 v169, v167
	v_mov_b32_e32 v172, v170
	v_mov_b32_e32 v173, v171
	v_mov_b32_e32 v176, v174
	v_mov_b32_e32 v177, v175
	v_mov_b32_e32 v180, v178
	v_mov_b32_e32 v181, v179
	v_mov_b32_e32 v184, v182
	v_mov_b32_e32 v185, v183
	v_mov_b32_e32 v188, v186
	v_mov_b32_e32 v189, v187
	v_mov_b32_e32 v192, v190
	v_mov_b32_e32 v193, v191
	s_nop 1
	v_permlane32_swap_b32_e32 v162, v164
	v_permlane32_swap_b32_e32 v163, v165
	v_permlane32_swap_b32_e32 v166, v168
	v_permlane32_swap_b32_e32 v167, v169
	v_permlane32_swap_b32_e32 v170, v172
	v_permlane32_swap_b32_e32 v171, v173
	v_permlane32_swap_b32_e32 v174, v176
	v_permlane32_swap_b32_e32 v175, v177
	v_permlane32_swap_b32_e32 v178, v180
	v_permlane32_swap_b32_e32 v179, v181
	v_permlane32_swap_b32_e32 v182, v184
	v_permlane32_swap_b32_e32 v183, v185
	v_permlane32_swap_b32_e32 v186, v188
	v_permlane32_swap_b32_e32 v187, v189
	v_permlane32_swap_b32_e32 v190, v192
	v_permlane32_swap_b32_e32 v191, v193
	v_add_f32_e32 v162, v162, v163
	v_add_f32_e32 v166, v166, v167
	v_add_f32_e32 v170, v170, v171
	v_add_f32_e32 v174, v174, v175
	v_add_f32_e32 v178, v178, v179
	v_add_f32_e32 v182, v182, v183
	v_add_f32_e32 v186, v186, v187
	v_add_f32_e32 v190, v190, v191
	v_add_f32_e32 v162, v162, v164
	v_add_f32_e32 v166, v166, v168
	v_add_f32_e32 v170, v170, v172
	v_add_f32_e32 v174, v174, v176
	v_add_f32_e32 v178, v178, v180
	v_add_f32_e32 v182, v182, v184
	v_add_f32_e32 v186, v186, v188
	v_add_f32_e32 v190, v190, v192
	v_add_f32_e32 v162, v162, v165
	v_add_f32_e32 v166, v166, v169
	v_add_f32_e32 v170, v170, v173
	v_add_f32_e32 v174, v174, v177
	v_add_f32_e32 v178, v178, v181
	v_add_f32_e32 v182, v182, v185
	v_add_f32_e32 v186, v186, v189
	v_add_f32_e32 v190, v190, v193
	v_fmamk_f32 v204, v162, 0x3a800000, v159
	v_mul_f32_e32 v205, 0x4f800000, v204
	v_cmp_gt_f32_e32 vcc, s57, v204
	s_nop 0
	s_nop 0
	v_cndmask_b32_e32 v204, v204, v205, vcc
	v_sqrt_f32_e32 v205, v204
	s_nop 0
	v_add_u32_e32 v206, -1, v205
	v_add_u32_e32 v207, 1, v205
	v_fma_f32 v208, -v206, v205, v204
	v_fma_f32 v209, -v207, v205, v204
	v_cmp_ge_f32_e64 s[6:7], 0, v208
	s_nop 1
	v_cndmask_b32_e64 v206, v205, v206, s[6:7]
	v_cmp_lt_f32_e64 s[6:7], 0, v209
	s_nop 1
	v_cndmask_b32_e64 v206, v206, v207, s[6:7]
	v_mul_f32_e32 v205, 0x37800000, v206
	v_cndmask_b32_e32 v206, v206, v205, vcc
	v_cmp_class_f32_e32 vcc, v204, v160
	s_nop 1
	v_cndmask_b32_e32 v204, v206, v204, vcc
	v_div_scale_f32 v206, s[6:7], v204, v204, 1.0
	v_rcp_f32_e32 v205, v206
	v_div_scale_f32 v207, vcc, 1.0, v204, 1.0
	v_fma_f32 v208, -v206, v205, 1.0
	v_fmac_f32_e32 v205, v208, v205
	v_mul_f32_e32 v208, v207, v205
	v_fma_f32 v209, -v206, v208, v207
	v_fmac_f32_e32 v208, v209, v205
	v_fma_f32 v206, -v206, v208, v207
	v_div_fmas_f32 v206, v206, v205, v208
	v_div_fixup_f32 v162, v206, v204, 1.0
	v_pk_mul_f32 v[126:127], v[126:127], v[162:163] op_sel_hi:[1,0]
	v_pk_mul_f32 v[128:129], v[128:129], v[162:163] op_sel_hi:[1,0]
	v_pk_mul_f32 v[122:123], v[122:123], v[162:163] op_sel_hi:[1,0]
	v_pk_mul_f32 v[124:125], v[124:125], v[162:163] op_sel_hi:[1,0]
	v_pk_mul_f32 v[118:119], v[118:119], v[162:163] op_sel_hi:[1,0]
	v_pk_mul_f32 v[114:115], v[114:115], v[162:163] op_sel_hi:[1,0]
	v_pk_mul_f32 v[120:121], v[120:121], v[162:163] op_sel_hi:[1,0]
	v_pk_mul_f32 v[116:117], v[116:117], v[162:163] op_sel_hi:[1,0]
	v_mul_f32_e32 v204, 0xbfb8aa3b, v126
	v_mul_f32_e32 v205, 0xbfb8aa3b, v127
	v_mul_f32_e32 v206, 0xbfb8aa3b, v128
	v_mul_f32_e32 v207, 0xbfb8aa3b, v129
	v_mul_f32_e32 v208, 0xbfb8aa3b, v118
	v_mul_f32_e32 v209, 0xbfb8aa3b, v119
	v_mul_f32_e32 v210, 0xbfb8aa3b, v120
	v_mul_f32_e32 v211, 0xbfb8aa3b, v121
	v_exp_f32_e32 v204, v204
	v_exp_f32_e32 v205, v205
	v_exp_f32_e32 v206, v206
	v_exp_f32_e32 v207, v207
	v_exp_f32_e32 v208, v208
	v_exp_f32_e32 v209, v209
	v_exp_f32_e32 v210, v210
	v_exp_f32_e32 v211, v211
	v_add_f32_e32 v204, 1.0, v204
	v_add_f32_e32 v205, 1.0, v205
	v_add_f32_e32 v206, 1.0, v206
	v_add_f32_e32 v207, 1.0, v207
	v_add_f32_e32 v208, 1.0, v208
	v_add_f32_e32 v209, 1.0, v209
	v_add_f32_e32 v210, 1.0, v210
	v_add_f32_e32 v211, 1.0, v211
	v_rcp_f32_e32 v212, v204
	v_rcp_f32_e32 v213, v205
	v_rcp_f32_e32 v214, v206
	v_rcp_f32_e32 v215, v207
	v_rcp_f32_e32 v216, v208
	v_rcp_f32_e32 v217, v209
; DI unsigned pk2(float lo, float hi) { const f32x2 v = {lo, hi}; const bf16x2_t b = __builtin_convertvector(v, bf16x2_t); return __builtin_bit_cast(unsigned, b); }
; DI float sigmoidf_(float x) { return __builtin_amdgcn_rcpf(1.0f + __expf(-x)); }
;     DI void operator()(const Acc& acc, const Unit& u, int wr, int wc, int fr, int fq) const {
;     ...
;                 const int r = row0 + ai * 128 + m * 16;
;                 const f32x4* sp = (const f32x4*)(SS + (size_t)r * 16);
;                 const f32x4 s0 = sp[0], s1 = sp[1], s2 = sp[2], s3 = sp[3];
;                 const float tot = ((s0[0] + s0[1]) + (s0[2] + s0[3])) + ((s1[0] + s1[1]) + (s1[2] + s1[3])) + ((s2[0] + s2[1]) + (s2[2] + s2[3])) + ((s3[0] + s3[1]) + (s3[2] + s3[3]));
;                 const float rr = 1.0f / sqrtf(tot * (1.0f / DM) + EPS);
; #pragma unroll
;                 for (int bj = 0; bj < 2; ++bj) {
;                     const int f0 = u.pn * 128 + bj * 64 + wc * 16 + 4 * fq;
;                     const f32x4 g = acc[ai][bj][m][0] * rr, up = acc[ai][bj][m][1] * rr;
;                     float o[4];
; #pragma unroll
;                     for (int i = 0; i < 4; ++i) o[i] = g[i] * sigmoidf_(g[i]) * up[i];
;                     u32x2 w; w.x = pk2(o[0], o[1]); w.y = pk2(o[2], o[3]);
;                     *(u32x2*)(ACT + (size_t)r * DFF + f0) = w;
	v_rcp_f32_e32 v218, v210
	v_rcp_f32_e32 v219, v211
	v_pk_mul_f32 v[126:127], v[126:127], v[212:213]
	v_pk_mul_f32 v[128:129], v[128:129], v[214:215]
	v_pk_mul_f32 v[118:119], v[118:119], v[216:217]
	v_pk_mul_f32 v[120:121], v[120:121], v[218:219]
	v_pk_mul_f32 v[122:123], v[122:123], v[126:127]
	v_pk_mul_f32 v[124:125], v[124:125], v[128:129]
	v_pk_mul_f32 v[114:115], v[114:115], v[118:119]
	v_pk_mul_f32 v[116:117], v[116:117], v[120:121]
	v_cvt_pk_bf16_f32 v118, v122, v123
	v_cvt_pk_bf16_f32 v119, v124, v125
	v_cvt_pk_bf16_f32 v114, v114, v115
	v_cvt_pk_bf16_f32 v115, v116, v117
	global_store_dwordx2 v161, v[118:119], s[22:23]
	global_store_dwordx2 v161, v[114:115], s[22:23] offset:128
	v_fmamk_f32 v204, v166, 0x3a800000, v159
	v_mul_f32_e32 v205, 0x4f800000, v204
	v_cmp_gt_f32_e32 vcc, s57, v204
	v_add_u32_e32 v220, 0x16000, v161
	s_nop 0
	v_cndmask_b32_e32 v204, v204, v205, vcc
	v_sqrt_f32_e32 v205, v204
	s_nop 0
	v_add_u32_e32 v206, -1, v205
	v_add_u32_e32 v207, 1, v205
	v_fma_f32 v208, -v206, v205, v204
	v_fma_f32 v209, -v207, v205, v204
	v_cmp_ge_f32_e64 s[6:7], 0, v208
	s_nop 1
	v_cndmask_b32_e64 v206, v205, v206, s[6:7]
	v_cmp_lt_f32_e64 s[6:7], 0, v209
	s_nop 1
	v_cndmask_b32_e64 v206, v206, v207, s[6:7]
	v_mul_f32_e32 v205, 0x37800000, v206
	v_cndmask_b32_e32 v206, v206, v205, vcc
	v_cmp_class_f32_e32 vcc, v204, v160
	s_nop 1
	v_cndmask_b32_e32 v204, v206, v204, vcc
	v_div_scale_f32 v206, s[6:7], v204, v204, 1.0
	v_rcp_f32_e32 v205, v206
	v_div_scale_f32 v207, vcc, 1.0, v204, 1.0
	v_fma_f32 v208, -v206, v205, 1.0
	v_fmac_f32_e32 v205, v208, v205
	v_mul_f32_e32 v208, v207, v205
	v_fma_f32 v209, -v206, v208, v207
	v_fmac_f32_e32 v208, v209, v205
	v_fma_f32 v206, -v206, v208, v207
	v_div_fmas_f32 v206, v206, v205, v208
	v_div_fixup_f32 v166, v206, v204, 1.0
	v_pk_mul_f32 v[110:111], v[110:111], v[166:167] op_sel_hi:[1,0]
	v_pk_mul_f32 v[112:113], v[112:113], v[166:167] op_sel_hi:[1,0]
	v_pk_mul_f32 v[106:107], v[106:107], v[166:167] op_sel_hi:[1,0]
	v_pk_mul_f32 v[108:109], v[108:109], v[166:167] op_sel_hi:[1,0]
	v_pk_mul_f32 v[102:103], v[102:103], v[166:167] op_sel_hi:[1,0]
	v_pk_mul_f32 v[98:99], v[98:99], v[166:167] op_sel_hi:[1,0]
	v_pk_mul_f32 v[104:105], v[104:105], v[166:167] op_sel_hi:[1,0]
	v_pk_mul_f32 v[100:101], v[100:101], v[166:167] op_sel_hi:[1,0]
	v_mul_f32_e32 v204, 0xbfb8aa3b, v110
	v_mul_f32_e32 v205, 0xbfb8aa3b, v111
	v_mul_f32_e32 v206, 0xbfb8aa3b, v112
	v_mul_f32_e32 v207, 0xbfb8aa3b, v113
	v_mul_f32_e32 v208, 0xbfb8aa3b, v102
	v_mul_f32_e32 v209, 0xbfb8aa3b, v103
	v_mul_f32_e32 v210, 0xbfb8aa3b, v104
	v_mul_f32_e32 v211, 0xbfb8aa3b, v105
	v_exp_f32_e32 v204, v204
	v_exp_f32_e32 v205, v205
	v_exp_f32_e32 v206, v206
	v_exp_f32_e32 v207, v207
	v_exp_f32_e32 v208, v208
	v_exp_f32_e32 v209, v209
	v_exp_f32_e32 v210, v210
	v_exp_f32_e32 v211, v211
	v_add_f32_e32 v204, 1.0, v204
	v_add_f32_e32 v205, 1.0, v205
	v_add_f32_e32 v206, 1.0, v206
	v_add_f32_e32 v207, 1.0, v207
	v_add_f32_e32 v208, 1.0, v208
	v_add_f32_e32 v209, 1.0, v209
	v_add_f32_e32 v210, 1.0, v210
	v_add_f32_e32 v211, 1.0, v211
	v_rcp_f32_e32 v212, v204
	v_rcp_f32_e32 v213, v205
	v_rcp_f32_e32 v214, v206
	v_rcp_f32_e32 v215, v207
	v_rcp_f32_e32 v216, v208
	v_rcp_f32_e32 v217, v209
	v_rcp_f32_e32 v218, v210
	v_rcp_f32_e32 v219, v211
	v_pk_mul_f32 v[110:111], v[110:111], v[212:213]
	v_pk_mul_f32 v[112:113], v[112:113], v[214:215]
	v_pk_mul_f32 v[102:103], v[102:103], v[216:217]
	v_pk_mul_f32 v[104:105], v[104:105], v[218:219]
	v_pk_mul_f32 v[106:107], v[106:107], v[110:111]
	v_pk_mul_f32 v[108:109], v[108:109], v[112:113]
	v_pk_mul_f32 v[98:99], v[98:99], v[102:103]
	v_pk_mul_f32 v[100:101], v[100:101], v[104:105]
	v_cvt_pk_bf16_f32 v102, v106, v107
	v_cvt_pk_bf16_f32 v103, v108, v109
	v_cvt_pk_bf16_f32 v98, v98, v99
	v_cvt_pk_bf16_f32 v99, v100, v101
	global_store_dwordx2 v220, v[102:103], s[22:23]
	global_store_dwordx2 v220, v[98:99], s[22:23] offset:128
	v_fmamk_f32 v204, v170, 0x3a800000, v159
	v_mul_f32_e32 v205, 0x4f800000, v204
	v_cmp_gt_f32_e32 vcc, s57, v204
	v_add_u32_e32 v220, 0x2c000, v161
	s_nop 0
	v_cndmask_b32_e32 v204, v204, v205, vcc
	v_sqrt_f32_e32 v205, v204
	s_nop 0
	v_add_u32_e32 v206, -1, v205
	v_add_u32_e32 v207, 1, v205
	v_fma_f32 v208, -v206, v205, v204
	v_fma_f32 v209, -v207, v205, v204
	v_cmp_ge_f32_e64 s[6:7], 0, v208
	s_nop 1
	v_cndmask_b32_e64 v206, v205, v206, s[6:7]
	v_cmp_lt_f32_e64 s[6:7], 0, v209
	s_nop 1
	v_cndmask_b32_e64 v206, v206, v207, s[6:7]
	v_mul_f32_e32 v205, 0x37800000, v206
	v_cndmask_b32_e32 v206, v206, v205, vcc
	v_cmp_class_f32_e32 vcc, v204, v160
	s_nop 1
	v_cndmask_b32_e32 v204, v206, v204, vcc
	v_div_scale_f32 v206, s[6:7], v204, v204, 1.0
	v_rcp_f32_e32 v205, v206
	v_div_scale_f32 v207, vcc, 1.0, v204, 1.0
	v_fma_f32 v208, -v206, v205, 1.0
	v_fmac_f32_e32 v205, v208, v205
	v_mul_f32_e32 v208, v207, v205
	v_fma_f32 v209, -v206, v208, v207
	v_fmac_f32_e32 v208, v209, v205
	v_fma_f32 v206, -v206, v208, v207
	v_div_fmas_f32 v206, v206, v205, v208
	v_div_fixup_f32 v170, v206, v204, 1.0
	v_pk_mul_f32 v[94:95], v[94:95], v[170:171] op_sel_hi:[1,0]
	v_pk_mul_f32 v[96:97], v[96:97], v[170:171] op_sel_hi:[1,0]
	v_pk_mul_f32 v[90:91], v[90:91], v[170:171] op_sel_hi:[1,0]
	v_pk_mul_f32 v[92:93], v[92:93], v[170:171] op_sel_hi:[1,0]
	v_pk_mul_f32 v[86:87], v[86:87], v[170:171] op_sel_hi:[1,0]
	v_pk_mul_f32 v[82:83], v[82:83], v[170:171] op_sel_hi:[1,0]
	v_pk_mul_f32 v[88:89], v[88:89], v[170:171] op_sel_hi:[1,0]
	v_pk_mul_f32 v[84:85], v[84:85], v[170:171] op_sel_hi:[1,0]
	v_mul_f32_e32 v204, 0xbfb8aa3b, v94
	v_mul_f32_e32 v205, 0xbfb8aa3b, v95
	v_mul_f32_e32 v206, 0xbfb8aa3b, v96
	v_mul_f32_e32 v207, 0xbfb8aa3b, v97
; DI unsigned pk2(float lo, float hi) { const f32x2 v = {lo, hi}; const bf16x2_t b = __builtin_convertvector(v, bf16x2_t); return __builtin_bit_cast(unsigned, b); }
; DI float sigmoidf_(float x) { return __builtin_amdgcn_rcpf(1.0f + __expf(-x)); }
;     DI void operator()(const Acc& acc, const Unit& u, int wr, int wc, int fr, int fq) const {
;     ...
;                 const int r = row0 + ai * 128 + m * 16;
;                 const f32x4* sp = (const f32x4*)(SS + (size_t)r * 16);
;                 const f32x4 s0 = sp[0], s1 = sp[1], s2 = sp[2], s3 = sp[3];
;                 const float tot = ((s0[0] + s0[1]) + (s0[2] + s0[3])) + ((s1[0] + s1[1]) + (s1[2] + s1[3])) + ((s2[0] + s2[1]) + (s2[2] + s2[3])) + ((s3[0] + s3[1]) + (s3[2] + s3[3]));
;                 const float rr = 1.0f / sqrtf(tot * (1.0f / DM) + EPS);
; #pragma unroll
;                 for (int bj = 0; bj < 2; ++bj) {
;                     const int f0 = u.pn * 128 + bj * 64 + wc * 16 + 4 * fq;
;                     const f32x4 g = acc[ai][bj][m][0] * rr, up = acc[ai][bj][m][1] * rr;
;                     float o[4];
; #pragma unroll
;                     for (int i = 0; i < 4; ++i) o[i] = g[i] * sigmoidf_(g[i]) * up[i];
;                     u32x2 w; w.x = pk2(o[0], o[1]); w.y = pk2(o[2], o[3]);
;                     *(u32x2*)(ACT + (size_t)r * DFF + f0) = w;
	v_mul_f32_e32 v208, 0xbfb8aa3b, v86
	v_mul_f32_e32 v209, 0xbfb8aa3b, v87
	v_mul_f32_e32 v210, 0xbfb8aa3b, v88
	v_mul_f32_e32 v211, 0xbfb8aa3b, v89
	v_exp_f32_e32 v204, v204
	v_exp_f32_e32 v205, v205
	v_exp_f32_e32 v206, v206
	v_exp_f32_e32 v207, v207
	v_exp_f32_e32 v208, v208
	v_exp_f32_e32 v209, v209
	v_exp_f32_e32 v210, v210
	v_exp_f32_e32 v211, v211
	v_add_f32_e32 v204, 1.0, v204
	v_add_f32_e32 v205, 1.0, v205
	v_add_f32_e32 v206, 1.0, v206
	v_add_f32_e32 v207, 1.0, v207
	v_add_f32_e32 v208, 1.0, v208
	v_add_f32_e32 v209, 1.0, v209
	v_add_f32_e32 v210, 1.0, v210
	v_add_f32_e32 v211, 1.0, v211
	v_rcp_f32_e32 v212, v204
	v_rcp_f32_e32 v213, v205
	v_rcp_f32_e32 v214, v206
	v_rcp_f32_e32 v215, v207
	v_rcp_f32_e32 v216, v208
	v_rcp_f32_e32 v217, v209
	v_rcp_f32_e32 v218, v210
	v_rcp_f32_e32 v219, v211
	v_pk_mul_f32 v[94:95], v[94:95], v[212:213]
	v_pk_mul_f32 v[96:97], v[96:97], v[214:215]
	v_pk_mul_f32 v[86:87], v[86:87], v[216:217]
	v_pk_mul_f32 v[88:89], v[88:89], v[218:219]
	v_pk_mul_f32 v[90:91], v[90:91], v[94:95]
	v_pk_mul_f32 v[92:93], v[92:93], v[96:97]
	v_pk_mul_f32 v[82:83], v[82:83], v[86:87]
	v_pk_mul_f32 v[84:85], v[84:85], v[88:89]
	v_cvt_pk_bf16_f32 v86, v90, v91
	v_cvt_pk_bf16_f32 v87, v92, v93
	v_cvt_pk_bf16_f32 v82, v82, v83
	v_cvt_pk_bf16_f32 v83, v84, v85
	global_store_dwordx2 v220, v[86:87], s[22:23]
	global_store_dwordx2 v220, v[82:83], s[22:23] offset:128
	v_fmamk_f32 v204, v174, 0x3a800000, v159
	v_mul_f32_e32 v205, 0x4f800000, v204
	v_cmp_gt_f32_e32 vcc, s57, v204
	v_add_u32_e32 v220, 0x42000, v161
	s_nop 0
	v_cndmask_b32_e32 v204, v204, v205, vcc
	v_sqrt_f32_e32 v205, v204
	s_nop 0
	v_add_u32_e32 v206, -1, v205
	v_add_u32_e32 v207, 1, v205
	v_fma_f32 v208, -v206, v205, v204
	v_fma_f32 v209, -v207, v205, v204
	v_cmp_ge_f32_e64 s[6:7], 0, v208
	s_nop 1
	v_cndmask_b32_e64 v206, v205, v206, s[6:7]
	v_cmp_lt_f32_e64 s[6:7], 0, v209
	s_nop 1
	v_cndmask_b32_e64 v206, v206, v207, s[6:7]
	v_mul_f32_e32 v205, 0x37800000, v206
	v_cndmask_b32_e32 v206, v206, v205, vcc
	v_cmp_class_f32_e32 vcc, v204, v160
	s_nop 1
	v_cndmask_b32_e32 v204, v206, v204, vcc
	v_div_scale_f32 v206, s[6:7], v204, v204, 1.0
	v_rcp_f32_e32 v205, v206
	v_div_scale_f32 v207, vcc, 1.0, v204, 1.0
	v_fma_f32 v208, -v206, v205, 1.0
	v_fmac_f32_e32 v205, v208, v205
	v_mul_f32_e32 v208, v207, v205
	v_fma_f32 v209, -v206, v208, v207
	v_fmac_f32_e32 v208, v209, v205
	v_fma_f32 v206, -v206, v208, v207
	v_div_fmas_f32 v206, v206, v205, v208
	v_div_fixup_f32 v174, v206, v204, 1.0
	v_pk_mul_f32 v[78:79], v[78:79], v[174:175] op_sel_hi:[1,0]
	v_pk_mul_f32 v[80:81], v[80:81], v[174:175] op_sel_hi:[1,0]
	v_pk_mul_f32 v[74:75], v[74:75], v[174:175] op_sel_hi:[1,0]
	v_pk_mul_f32 v[76:77], v[76:77], v[174:175] op_sel_hi:[1,0]
	v_pk_mul_f32 v[70:71], v[70:71], v[174:175] op_sel_hi:[1,0]
	v_pk_mul_f32 v[66:67], v[66:67], v[174:175] op_sel_hi:[1,0]
	v_pk_mul_f32 v[72:73], v[72:73], v[174:175] op_sel_hi:[1,0]
	v_pk_mul_f32 v[68:69], v[68:69], v[174:175] op_sel_hi:[1,0]
	v_mul_f32_e32 v204, 0xbfb8aa3b, v78
	v_mul_f32_e32 v205, 0xbfb8aa3b, v79
	v_mul_f32_e32 v206, 0xbfb8aa3b, v80
	v_mul_f32_e32 v207, 0xbfb8aa3b, v81
	v_mul_f32_e32 v208, 0xbfb8aa3b, v70
	v_mul_f32_e32 v209, 0xbfb8aa3b, v71
	v_mul_f32_e32 v210, 0xbfb8aa3b, v72
	v_mul_f32_e32 v211, 0xbfb8aa3b, v73
	v_exp_f32_e32 v204, v204
	v_exp_f32_e32 v205, v205
	v_exp_f32_e32 v206, v206
	v_exp_f32_e32 v207, v207
	v_exp_f32_e32 v208, v208
	v_exp_f32_e32 v209, v209
	v_exp_f32_e32 v210, v210
	v_exp_f32_e32 v211, v211
	v_add_f32_e32 v204, 1.0, v204
	v_add_f32_e32 v205, 1.0, v205
	v_add_f32_e32 v206, 1.0, v206
	v_add_f32_e32 v207, 1.0, v207
	v_add_f32_e32 v208, 1.0, v208
	v_add_f32_e32 v209, 1.0, v209
	v_add_f32_e32 v210, 1.0, v210
	v_add_f32_e32 v211, 1.0, v211
	v_rcp_f32_e32 v212, v204
	v_rcp_f32_e32 v213, v205
	v_rcp_f32_e32 v214, v206
	v_rcp_f32_e32 v215, v207
	v_rcp_f32_e32 v216, v208
	v_rcp_f32_e32 v217, v209
	v_rcp_f32_e32 v218, v210
	v_rcp_f32_e32 v219, v211
	v_pk_mul_f32 v[78:79], v[78:79], v[212:213]
	v_pk_mul_f32 v[80:81], v[80:81], v[214:215]
	v_pk_mul_f32 v[70:71], v[70:71], v[216:217]
	v_pk_mul_f32 v[72:73], v[72:73], v[218:219]
	v_pk_mul_f32 v[74:75], v[74:75], v[78:79]
	v_pk_mul_f32 v[76:77], v[76:77], v[80:81]
	v_pk_mul_f32 v[66:67], v[66:67], v[70:71]
	v_pk_mul_f32 v[68:69], v[68:69], v[72:73]
	v_cvt_pk_bf16_f32 v70, v74, v75
	v_cvt_pk_bf16_f32 v71, v76, v77
	v_cvt_pk_bf16_f32 v66, v66, v67
	v_cvt_pk_bf16_f32 v67, v68, v69
	global_store_dwordx2 v220, v[70:71], s[22:23]
	global_store_dwordx2 v220, v[66:67], s[22:23] offset:128
	v_fmamk_f32 v204, v178, 0x3a800000, v159
	v_mul_f32_e32 v205, 0x4f800000, v204
	v_cmp_gt_f32_e32 vcc, s57, v204
	v_add_u32_e32 v220, 0xb0000, v161
	s_nop 0
	v_cndmask_b32_e32 v204, v204, v205, vcc
	v_sqrt_f32_e32 v205, v204
	s_nop 0
	v_add_u32_e32 v206, -1, v205
	v_add_u32_e32 v207, 1, v205
	v_fma_f32 v208, -v206, v205, v204
	v_fma_f32 v209, -v207, v205, v204
	v_cmp_ge_f32_e64 s[6:7], 0, v208
	s_nop 1
	v_cndmask_b32_e64 v206, v205, v206, s[6:7]
	v_cmp_lt_f32_e64 s[6:7], 0, v209
	s_nop 1
	v_cndmask_b32_e64 v206, v206, v207, s[6:7]
	v_mul_f32_e32 v205, 0x37800000, v206
	v_cndmask_b32_e32 v206, v206, v205, vcc
	v_cmp_class_f32_e32 vcc, v204, v160
	s_nop 1
	v_cndmask_b32_e32 v204, v206, v204, vcc
	v_div_scale_f32 v206, s[6:7], v204, v204, 1.0
	v_rcp_f32_e32 v205, v206
	v_div_scale_f32 v207, vcc, 1.0, v204, 1.0
	v_fma_f32 v208, -v206, v205, 1.0
	v_fmac_f32_e32 v205, v208, v205
	v_mul_f32_e32 v208, v207, v205
	v_fma_f32 v209, -v206, v208, v207
	v_fmac_f32_e32 v208, v209, v205
	v_fma_f32 v206, -v206, v208, v207
	v_div_fmas_f32 v206, v206, v205, v208
	v_div_fixup_f32 v178, v206, v204, 1.0
; DI unsigned pk2(float lo, float hi) { const f32x2 v = {lo, hi}; const bf16x2_t b = __builtin_convertvector(v, bf16x2_t); return __builtin_bit_cast(unsigned, b); }
; DI float sigmoidf_(float x) { return __builtin_amdgcn_rcpf(1.0f + __expf(-x)); }
;     DI void operator()(const Acc& acc, const Unit& u, int wr, int wc, int fr, int fq) const {
;     ...
;                 const int r = row0 + ai * 128 + m * 16;
;                 const f32x4* sp = (const f32x4*)(SS + (size_t)r * 16);
;                 const f32x4 s0 = sp[0], s1 = sp[1], s2 = sp[2], s3 = sp[3];
;                 const float tot = ((s0[0] + s0[1]) + (s0[2] + s0[3])) + ((s1[0] + s1[1]) + (s1[2] + s1[3])) + ((s2[0] + s2[1]) + (s2[2] + s2[3])) + ((s3[0] + s3[1]) + (s3[2] + s3[3]));
;                 const float rr = 1.0f / sqrtf(tot * (1.0f / DM) + EPS);
; #pragma unroll
;                 for (int bj = 0; bj < 2; ++bj) {
;                     const int f0 = u.pn * 128 + bj * 64 + wc * 16 + 4 * fq;
;                     const f32x4 g = acc[ai][bj][m][0] * rr, up = acc[ai][bj][m][1] * rr;
;                     float o[4];
; #pragma unroll
;                     for (int i = 0; i < 4; ++i) o[i] = g[i] * sigmoidf_(g[i]) * up[i];
;                     u32x2 w; w.x = pk2(o[0], o[1]); w.y = pk2(o[2], o[3]);
;                     *(u32x2*)(ACT + (size_t)r * DFF + f0) = w;
	v_pk_mul_f32 v[62:63], v[62:63], v[178:179] op_sel_hi:[1,0]
	v_pk_mul_f32 v[64:65], v[64:65], v[178:179] op_sel_hi:[1,0]
	v_pk_mul_f32 v[58:59], v[58:59], v[178:179] op_sel_hi:[1,0]
	v_pk_mul_f32 v[60:61], v[60:61], v[178:179] op_sel_hi:[1,0]
	v_pk_mul_f32 v[54:55], v[54:55], v[178:179] op_sel_hi:[1,0]
	v_pk_mul_f32 v[50:51], v[50:51], v[178:179] op_sel_hi:[1,0]
	v_pk_mul_f32 v[56:57], v[56:57], v[178:179] op_sel_hi:[1,0]
	v_pk_mul_f32 v[52:53], v[52:53], v[178:179] op_sel_hi:[1,0]
	v_mul_f32_e32 v204, 0xbfb8aa3b, v62
	v_mul_f32_e32 v205, 0xbfb8aa3b, v63
	v_mul_f32_e32 v206, 0xbfb8aa3b, v64
	v_mul_f32_e32 v207, 0xbfb8aa3b, v65
	v_mul_f32_e32 v208, 0xbfb8aa3b, v54
	v_mul_f32_e32 v209, 0xbfb8aa3b, v55
	v_mul_f32_e32 v210, 0xbfb8aa3b, v56
	v_mul_f32_e32 v211, 0xbfb8aa3b, v57
	v_exp_f32_e32 v204, v204
	v_exp_f32_e32 v205, v205
	v_exp_f32_e32 v206, v206
	v_exp_f32_e32 v207, v207
	v_exp_f32_e32 v208, v208
	v_exp_f32_e32 v209, v209
	v_exp_f32_e32 v210, v210
	v_exp_f32_e32 v211, v211
	v_add_f32_e32 v204, 1.0, v204
	v_add_f32_e32 v205, 1.0, v205
	v_add_f32_e32 v206, 1.0, v206
	v_add_f32_e32 v207, 1.0, v207
	v_add_f32_e32 v208, 1.0, v208
	v_add_f32_e32 v209, 1.0, v209
	v_add_f32_e32 v210, 1.0, v210
	v_add_f32_e32 v211, 1.0, v211
	v_rcp_f32_e32 v212, v204
	v_rcp_f32_e32 v213, v205
	v_rcp_f32_e32 v214, v206
	v_rcp_f32_e32 v215, v207
	v_rcp_f32_e32 v216, v208
	v_rcp_f32_e32 v217, v209
	v_rcp_f32_e32 v218, v210
	v_rcp_f32_e32 v219, v211
	v_pk_mul_f32 v[62:63], v[62:63], v[212:213]
	v_pk_mul_f32 v[64:65], v[64:65], v[214:215]
	v_pk_mul_f32 v[54:55], v[54:55], v[216:217]
	v_pk_mul_f32 v[56:57], v[56:57], v[218:219]
	v_pk_mul_f32 v[58:59], v[58:59], v[62:63]
	v_pk_mul_f32 v[60:61], v[60:61], v[64:65]
	v_pk_mul_f32 v[50:51], v[50:51], v[54:55]
	v_pk_mul_f32 v[52:53], v[52:53], v[56:57]
	v_cvt_pk_bf16_f32 v54, v58, v59
	v_cvt_pk_bf16_f32 v55, v60, v61
	v_cvt_pk_bf16_f32 v50, v50, v51
	v_cvt_pk_bf16_f32 v51, v52, v53
	global_store_dwordx2 v220, v[54:55], s[22:23]
	global_store_dwordx2 v220, v[50:51], s[22:23] offset:128
	v_fmamk_f32 v204, v182, 0x3a800000, v159
	v_mul_f32_e32 v205, 0x4f800000, v204
	v_cmp_gt_f32_e32 vcc, s57, v204
	v_add_u32_e32 v220, 0xc6000, v161
	s_nop 0
	v_cndmask_b32_e32 v204, v204, v205, vcc
	v_sqrt_f32_e32 v205, v204
	s_nop 0
	v_add_u32_e32 v206, -1, v205
	v_add_u32_e32 v207, 1, v205
	v_fma_f32 v208, -v206, v205, v204
	v_fma_f32 v209, -v207, v205, v204
	v_cmp_ge_f32_e64 s[6:7], 0, v208
	s_nop 1
	v_cndmask_b32_e64 v206, v205, v206, s[6:7]
	v_cmp_lt_f32_e64 s[6:7], 0, v209
	s_nop 1
	v_cndmask_b32_e64 v206, v206, v207, s[6:7]
	v_mul_f32_e32 v205, 0x37800000, v206
	v_cndmask_b32_e32 v206, v206, v205, vcc
	v_cmp_class_f32_e32 vcc, v204, v160
	s_nop 1
	v_cndmask_b32_e32 v204, v206, v204, vcc
	v_div_scale_f32 v206, s[6:7], v204, v204, 1.0
	v_rcp_f32_e32 v205, v206
	v_div_scale_f32 v207, vcc, 1.0, v204, 1.0
	v_fma_f32 v208, -v206, v205, 1.0
	v_fmac_f32_e32 v205, v208, v205
	v_mul_f32_e32 v208, v207, v205
	v_fma_f32 v209, -v206, v208, v207
	v_fmac_f32_e32 v208, v209, v205
	v_fma_f32 v206, -v206, v208, v207
	v_div_fmas_f32 v206, v206, v205, v208
	v_div_fixup_f32 v182, v206, v204, 1.0
	v_pk_mul_f32 v[46:47], v[46:47], v[182:183] op_sel_hi:[1,0]
	v_pk_mul_f32 v[48:49], v[48:49], v[182:183] op_sel_hi:[1,0]
	v_pk_mul_f32 v[42:43], v[42:43], v[182:183] op_sel_hi:[1,0]
	v_pk_mul_f32 v[44:45], v[44:45], v[182:183] op_sel_hi:[1,0]
	v_pk_mul_f32 v[38:39], v[38:39], v[182:183] op_sel_hi:[1,0]
	v_pk_mul_f32 v[34:35], v[34:35], v[182:183] op_sel_hi:[1,0]
	v_pk_mul_f32 v[40:41], v[40:41], v[182:183] op_sel_hi:[1,0]
	v_pk_mul_f32 v[36:37], v[36:37], v[182:183] op_sel_hi:[1,0]
	v_mul_f32_e32 v204, 0xbfb8aa3b, v46
	v_mul_f32_e32 v205, 0xbfb8aa3b, v47
	v_mul_f32_e32 v206, 0xbfb8aa3b, v48
	v_mul_f32_e32 v207, 0xbfb8aa3b, v49
	v_mul_f32_e32 v208, 0xbfb8aa3b, v38
	v_mul_f32_e32 v209, 0xbfb8aa3b, v39
	v_mul_f32_e32 v210, 0xbfb8aa3b, v40
	v_mul_f32_e32 v211, 0xbfb8aa3b, v41
	v_exp_f32_e32 v204, v204
	v_exp_f32_e32 v205, v205
	v_exp_f32_e32 v206, v206
	v_exp_f32_e32 v207, v207
	v_exp_f32_e32 v208, v208
	v_exp_f32_e32 v209, v209
	v_exp_f32_e32 v210, v210
	v_exp_f32_e32 v211, v211
	v_add_f32_e32 v204, 1.0, v204
	v_add_f32_e32 v205, 1.0, v205
	v_add_f32_e32 v206, 1.0, v206
	v_add_f32_e32 v207, 1.0, v207
	v_add_f32_e32 v208, 1.0, v208
	v_add_f32_e32 v209, 1.0, v209
	v_add_f32_e32 v210, 1.0, v210
	v_add_f32_e32 v211, 1.0, v211
	v_rcp_f32_e32 v212, v204
	v_rcp_f32_e32 v213, v205
	v_rcp_f32_e32 v214, v206
	v_rcp_f32_e32 v215, v207
	v_rcp_f32_e32 v216, v208
	v_rcp_f32_e32 v217, v209
	v_rcp_f32_e32 v218, v210
	v_rcp_f32_e32 v219, v211
	v_pk_mul_f32 v[46:47], v[46:47], v[212:213]
	v_pk_mul_f32 v[48:49], v[48:49], v[214:215]
	v_pk_mul_f32 v[38:39], v[38:39], v[216:217]
	v_pk_mul_f32 v[40:41], v[40:41], v[218:219]
	v_pk_mul_f32 v[42:43], v[42:43], v[46:47]
	v_pk_mul_f32 v[44:45], v[44:45], v[48:49]
	v_pk_mul_f32 v[34:35], v[34:35], v[38:39]
	v_pk_mul_f32 v[36:37], v[36:37], v[40:41]
	v_cvt_pk_bf16_f32 v38, v42, v43
	v_cvt_pk_bf16_f32 v39, v44, v45
	v_cvt_pk_bf16_f32 v34, v34, v35
	v_cvt_pk_bf16_f32 v35, v36, v37
	global_store_dwordx2 v220, v[38:39], s[22:23]
	global_store_dwordx2 v220, v[34:35], s[22:23] offset:128
	v_fmamk_f32 v204, v186, 0x3a800000, v159
	v_mul_f32_e32 v205, 0x4f800000, v204
	v_cmp_gt_f32_e32 vcc, s57, v204
	v_add_u32_e32 v220, 0xdc000, v161
	s_nop 0
	v_cndmask_b32_e32 v204, v204, v205, vcc
	v_sqrt_f32_e32 v205, v204
	s_nop 0
	v_add_u32_e32 v206, -1, v205
	v_add_u32_e32 v207, 1, v205
	v_fma_f32 v208, -v206, v205, v204
	v_fma_f32 v209, -v207, v205, v204
	v_cmp_ge_f32_e64 s[6:7], 0, v208
	s_nop 1
	v_cndmask_b32_e64 v206, v205, v206, s[6:7]
; DI unsigned pk2(float lo, float hi) { const f32x2 v = {lo, hi}; const bf16x2_t b = __builtin_convertvector(v, bf16x2_t); return __builtin_bit_cast(unsigned, b); }
; DI float sigmoidf_(float x) { return __builtin_amdgcn_rcpf(1.0f + __expf(-x)); }
; #define PG8_BAR __builtin_amdgcn_s_barrier()
; template <class Epi, bool HOOK = false>
; DI void gemm_phase(LAS unsigned char* lds, const Gemm g, const StaticOrder& S, const Epi& E) {
;     ...
;         if (!has_next) break;
; #pragma unroll
;         for (int a = 0; a < 2; ++a)
; #pragma unroll
;             for (int b = 0; b < 2; ++b)
; #pragma unroll
;                 for (int m = 0; m < 4; ++m)
; #pragma unroll
;                     for (int n = 0; n < 2; ++n) acc[a][b][m][n] = (f32x4){0.f, 0.f, 0.f, 0.f};
;         cur = nxt; cA = nA; cB = nB; ++ui;
;         if (wr == 1) PG8_BAR;
;     }
;     DI void operator()(const Acc& acc, const Unit& u, int wr, int wc, int fr, int fq) const {
;     ...
;                 const int r = row0 + ai * 128 + m * 16;
;                 const f32x4* sp = (const f32x4*)(SS + (size_t)r * 16);
;                 const f32x4 s0 = sp[0], s1 = sp[1], s2 = sp[2], s3 = sp[3];
;                 const float tot = ((s0[0] + s0[1]) + (s0[2] + s0[3])) + ((s1[0] + s1[1]) + (s1[2] + s1[3])) + ((s2[0] + s2[1]) + (s2[2] + s2[3])) + ((s3[0] + s3[1]) + (s3[2] + s3[3]));
;                 const float rr = 1.0f / sqrtf(tot * (1.0f / DM) + EPS);
; #pragma unroll
;                 for (int bj = 0; bj < 2; ++bj) {
;                     const int f0 = u.pn * 128 + bj * 64 + wc * 16 + 4 * fq;
;                     const f32x4 g = acc[ai][bj][m][0] * rr, up = acc[ai][bj][m][1] * rr;
;                     float o[4];
; #pragma unroll
;                     for (int i = 0; i < 4; ++i) o[i] = g[i] * sigmoidf_(g[i]) * up[i];
;                     u32x2 w; w.x = pk2(o[0], o[1]); w.y = pk2(o[2], o[3]);
;                     *(u32x2*)(ACT + (size_t)r * DFF + f0) = w;
	v_cmp_lt_f32_e64 s[6:7], 0, v209
	s_nop 1
	v_cndmask_b32_e64 v206, v206, v207, s[6:7]
	v_mul_f32_e32 v205, 0x37800000, v206
	v_cndmask_b32_e32 v206, v206, v205, vcc
	v_cmp_class_f32_e32 vcc, v204, v160
	s_nop 1
	v_cndmask_b32_e32 v204, v206, v204, vcc
	v_div_scale_f32 v206, s[6:7], v204, v204, 1.0
	v_rcp_f32_e32 v205, v206
	v_div_scale_f32 v207, vcc, 1.0, v204, 1.0
	v_fma_f32 v208, -v206, v205, 1.0
	v_fmac_f32_e32 v205, v208, v205
	v_mul_f32_e32 v208, v207, v205
	v_fma_f32 v209, -v206, v208, v207
	v_fmac_f32_e32 v208, v209, v205
	v_fma_f32 v206, -v206, v208, v207
	v_div_fmas_f32 v206, v206, v205, v208
	v_div_fixup_f32 v186, v206, v204, 1.0
	v_pk_mul_f32 v[30:31], v[30:31], v[186:187] op_sel_hi:[1,0]
	v_pk_mul_f32 v[32:33], v[32:33], v[186:187] op_sel_hi:[1,0]
	v_pk_mul_f32 v[26:27], v[26:27], v[186:187] op_sel_hi:[1,0]
	v_pk_mul_f32 v[28:29], v[28:29], v[186:187] op_sel_hi:[1,0]
	v_pk_mul_f32 v[22:23], v[22:23], v[186:187] op_sel_hi:[1,0]
	v_pk_mul_f32 v[18:19], v[18:19], v[186:187] op_sel_hi:[1,0]
	v_pk_mul_f32 v[24:25], v[24:25], v[186:187] op_sel_hi:[1,0]
	v_pk_mul_f32 v[20:21], v[20:21], v[186:187] op_sel_hi:[1,0]
	v_mul_f32_e32 v204, 0xbfb8aa3b, v30
	v_mul_f32_e32 v205, 0xbfb8aa3b, v31
	v_mul_f32_e32 v206, 0xbfb8aa3b, v32
	v_mul_f32_e32 v207, 0xbfb8aa3b, v33
	v_mul_f32_e32 v208, 0xbfb8aa3b, v22
	v_mul_f32_e32 v209, 0xbfb8aa3b, v23
	v_mul_f32_e32 v210, 0xbfb8aa3b, v24
	v_mul_f32_e32 v211, 0xbfb8aa3b, v25
	v_exp_f32_e32 v204, v204
	v_exp_f32_e32 v205, v205
	v_exp_f32_e32 v206, v206
	v_exp_f32_e32 v207, v207
	v_exp_f32_e32 v208, v208
	v_exp_f32_e32 v209, v209
	v_exp_f32_e32 v210, v210
	v_exp_f32_e32 v211, v211
	v_add_f32_e32 v204, 1.0, v204
	v_add_f32_e32 v205, 1.0, v205
	v_add_f32_e32 v206, 1.0, v206
	v_add_f32_e32 v207, 1.0, v207
	v_add_f32_e32 v208, 1.0, v208
	v_add_f32_e32 v209, 1.0, v209
	v_add_f32_e32 v210, 1.0, v210
	v_add_f32_e32 v211, 1.0, v211
	v_rcp_f32_e32 v212, v204
	v_rcp_f32_e32 v213, v205
	v_rcp_f32_e32 v214, v206
	v_rcp_f32_e32 v215, v207
	v_rcp_f32_e32 v216, v208
	v_rcp_f32_e32 v217, v209
	v_rcp_f32_e32 v218, v210
	v_rcp_f32_e32 v219, v211
	v_pk_mul_f32 v[30:31], v[30:31], v[212:213]
	v_pk_mul_f32 v[32:33], v[32:33], v[214:215]
	v_pk_mul_f32 v[22:23], v[22:23], v[216:217]
	v_pk_mul_f32 v[24:25], v[24:25], v[218:219]
	v_pk_mul_f32 v[26:27], v[26:27], v[30:31]
	v_pk_mul_f32 v[28:29], v[28:29], v[32:33]
	v_pk_mul_f32 v[18:19], v[18:19], v[22:23]
	v_pk_mul_f32 v[20:21], v[20:21], v[24:25]
	v_cvt_pk_bf16_f32 v22, v26, v27
	v_cvt_pk_bf16_f32 v23, v28, v29
	v_cvt_pk_bf16_f32 v18, v18, v19
	v_cvt_pk_bf16_f32 v19, v20, v21
	global_store_dwordx2 v220, v[22:23], s[22:23]
	global_store_dwordx2 v220, v[18:19], s[22:23] offset:128
	v_fmamk_f32 v204, v190, 0x3a800000, v159
	v_mul_f32_e32 v205, 0x4f800000, v204
	v_cmp_gt_f32_e32 vcc, s57, v204
	v_add_u32_e32 v220, 0xf2000, v161
	s_nop 0
	v_cndmask_b32_e32 v204, v204, v205, vcc
	v_sqrt_f32_e32 v205, v204
	s_nop 0
	v_add_u32_e32 v206, -1, v205
	v_add_u32_e32 v207, 1, v205
	v_fma_f32 v208, -v206, v205, v204
	v_fma_f32 v209, -v207, v205, v204
	v_cmp_ge_f32_e64 s[6:7], 0, v208
	s_nop 1
	v_cndmask_b32_e64 v206, v205, v206, s[6:7]
	v_cmp_lt_f32_e64 s[6:7], 0, v209
	s_nop 1
	v_cndmask_b32_e64 v206, v206, v207, s[6:7]
	v_mul_f32_e32 v205, 0x37800000, v206
	v_cndmask_b32_e32 v206, v206, v205, vcc
	v_cmp_class_f32_e32 vcc, v204, v160
	s_nop 1
	v_cndmask_b32_e32 v204, v206, v204, vcc
	v_div_scale_f32 v206, s[6:7], v204, v204, 1.0
	v_rcp_f32_e32 v205, v206
	v_div_scale_f32 v207, vcc, 1.0, v204, 1.0
	v_fma_f32 v208, -v206, v205, 1.0
	v_fmac_f32_e32 v205, v208, v205
	v_mul_f32_e32 v208, v207, v205
	v_fma_f32 v209, -v206, v208, v207
	v_fmac_f32_e32 v208, v209, v205
	v_fma_f32 v206, -v206, v208, v207
	v_div_fmas_f32 v206, v206, v205, v208
	v_div_fixup_f32 v190, v206, v204, 1.0
	v_pk_mul_f32 v[14:15], v[14:15], v[190:191] op_sel_hi:[1,0]
	v_pk_mul_f32 v[16:17], v[16:17], v[190:191] op_sel_hi:[1,0]
	v_pk_mul_f32 v[10:11], v[10:11], v[190:191] op_sel_hi:[1,0]
	v_pk_mul_f32 v[12:13], v[12:13], v[190:191] op_sel_hi:[1,0]
	v_pk_mul_f32 v[6:7], v[6:7], v[190:191] op_sel_hi:[1,0]
	v_pk_mul_f32 v[2:3], v[2:3], v[190:191] op_sel_hi:[1,0]
	v_pk_mul_f32 v[8:9], v[8:9], v[190:191] op_sel_hi:[1,0]
	v_pk_mul_f32 v[4:5], v[4:5], v[190:191] op_sel_hi:[1,0]
	v_mul_f32_e32 v204, 0xbfb8aa3b, v14
	v_mul_f32_e32 v205, 0xbfb8aa3b, v15
	v_mul_f32_e32 v206, 0xbfb8aa3b, v16
	v_mul_f32_e32 v207, 0xbfb8aa3b, v17
	v_mul_f32_e32 v208, 0xbfb8aa3b, v6
	v_mul_f32_e32 v209, 0xbfb8aa3b, v7
	v_mul_f32_e32 v210, 0xbfb8aa3b, v8
	v_mul_f32_e32 v211, 0xbfb8aa3b, v9
	v_exp_f32_e32 v204, v204
	v_exp_f32_e32 v205, v205
	v_exp_f32_e32 v206, v206
	v_exp_f32_e32 v207, v207
	v_exp_f32_e32 v208, v208
	v_exp_f32_e32 v209, v209
	v_exp_f32_e32 v210, v210
	v_exp_f32_e32 v211, v211
	v_add_f32_e32 v204, 1.0, v204
	v_add_f32_e32 v205, 1.0, v205
	v_add_f32_e32 v206, 1.0, v206
	v_add_f32_e32 v207, 1.0, v207
	v_add_f32_e32 v208, 1.0, v208
	v_add_f32_e32 v209, 1.0, v209
	v_add_f32_e32 v210, 1.0, v210
	v_add_f32_e32 v211, 1.0, v211
	v_rcp_f32_e32 v212, v204
	v_rcp_f32_e32 v213, v205
	v_rcp_f32_e32 v214, v206
	v_rcp_f32_e32 v215, v207
	v_rcp_f32_e32 v216, v208
	v_rcp_f32_e32 v217, v209
	v_rcp_f32_e32 v218, v210
	v_rcp_f32_e32 v219, v211
	v_pk_mul_f32 v[14:15], v[14:15], v[212:213]
	v_pk_mul_f32 v[16:17], v[16:17], v[214:215]
	v_pk_mul_f32 v[6:7], v[6:7], v[216:217]
	v_pk_mul_f32 v[8:9], v[8:9], v[218:219]
	v_pk_mul_f32 v[10:11], v[10:11], v[14:15]
	v_pk_mul_f32 v[12:13], v[12:13], v[16:17]
	v_pk_mul_f32 v[2:3], v[2:3], v[6:7]
	v_pk_mul_f32 v[4:5], v[4:5], v[8:9]
	v_cvt_pk_bf16_f32 v6, v10, v11
	v_cvt_pk_bf16_f32 v7, v12, v13
	v_cvt_pk_bf16_f32 v2, v2, v3
	v_cvt_pk_bf16_f32 v3, v4, v5
	global_store_dwordx2 v220, v[6:7], s[22:23]
	global_store_dwordx2 v220, v[2:3], s[22:23] offset:128
	s_andn2_b64 vcc, exec, s[4:5]
	s_mov_b64 s[4:5], -1
	s_cbranch_vccnz .LBB0_1030
	s_andn2_b64 vcc, exec, s[10:11]
	s_cbranch_vccnz .LBB0_1029
	s_barrier
	s_branch .LBB0_1029
